# prologue: x to bf16 conversion loop de-serialised - all 32 row loads of a wave are issued first, rows converted behind counted vmcnt waits (was load / drain / store four times per row)
# speedup vs baseline: 1.0017x; 1.0017x over previous
.LBB0_96:
	v_readlane_b32 s1, v252, 8
	s_lshr_b32 s0, s3, 6
	s_lshl_b32 s1, s1, 2
	s_add_i32 s0, s1, s0
	s_cmpk_lt_i32 s0, 0x4000
	s_cselect_b64 s[4:5], -1, 0
	v_writelane_b32 v252, s4, 29
	s_lshl_b32 s60, s90, 2
	s_mov_b32 s52, s0
	v_writelane_b32 v252, s5, 30
	s_cmpk_gt_i32 s0, 0x3fff
	v_mbcnt_lo_u32_b32 v1, -1, 0
	s_cbranch_scc1 .LBB0_101
	v_mbcnt_hi_u32_b32 v2, -1, v1
	v_and_b32_e32 v4, 64, v2
	v_xor_b32_e32 v3, 32, v2
	v_add_u32_e32 v4, 64, v4
	v_cmp_lt_i32_e32 vcc, v3, v4
	v_and_b32_e32 v14, 63, v197
	s_mov_b32 s14, s52
	v_cndmask_b32_e32 v3, v2, v3, vcc
	v_lshlrev_b32_e32 v8, 2, v3
	v_xor_b32_e32 v3, 16, v2
	v_cmp_lt_i32_e32 vcc, v3, v4
	s_ashr_i32 s15, s52, 31
	v_lshlrev_b32_e32 v6, 2, v14
	v_cndmask_b32_e32 v3, v2, v3, vcc
	v_lshlrev_b32_e32 v9, 2, v3
	v_xor_b32_e32 v3, 8, v2
	v_cmp_lt_i32_e32 vcc, v3, v4
	v_mov_b32_e32 v7, 0
	s_lshl_b64 s[6:7], s[14:15], 6
	v_cndmask_b32_e32 v3, v2, v3, vcc
	v_lshlrev_b32_e32 v10, 2, v3
	v_xor_b32_e32 v3, 4, v2
	v_cmp_lt_i32_e32 vcc, v3, v4
	s_ashr_i32 s61, s60, 31
	s_lshl_b64 s[10:11], s[14:15], 11
	v_cndmask_b32_e32 v3, v2, v3, vcc
	v_lshlrev_b32_e32 v11, 2, v3
	v_xor_b32_e32 v3, 2, v2
	v_cmp_lt_i32_e32 vcc, v3, v4
	v_mov_b32_e32 v5, s11
	s_lshl_b64 s[12:13], s[14:15], 12
	v_cndmask_b32_e32 v3, v2, v3, vcc
	v_lshlrev_b32_e32 v12, 2, v3
	v_xor_b32_e32 v3, 1, v2
	v_cmp_lt_i32_e32 vcc, v3, v4
	v_lshl_or_b32 v4, v14, 3, s10
	s_lshl_b64 s[10:11], s[60:61], 11
	v_cndmask_b32_e32 v2, v2, v3, vcc
	v_lshlrev_b32_e32 v13, 2, v2
	v_lshl_add_u64 v[2:3], s[6:7], 0, v[6:7]
	s_lshl_b64 s[6:7], s[60:61], 6
	s_add_u32 s12, s64, s12
	v_lshlrev_b32_e32 v6, 4, v14
	s_addc_u32 s13, s65, s13
	v_lshl_add_u64 v[6:7], s[12:13], 0, v[6:7]
	s_mov_b64 s[12:13], 0x800
	v_cmp_gt_u32_e64 s[0:1], 16, v14
	v_cmp_eq_u32_e64 s[4:5], 0, v14
	v_lshl_add_u64 v[6:7], v[6:7], 0, s[12:13]
	s_lshl_b64 s[12:13], s[60:61], 12
	s_mov_b32 s3, 0x7300000
	s_mov_b32 s16, s52
	global_load_dwordx4 v[32:35], v[6:7], off offset:-2048
	global_load_dwordx4 v[36:39], v[6:7], off offset:-1024
	global_load_dwordx4 v[40:43], v[6:7], off
	global_load_dwordx4 v[44:47], v[6:7], off offset:1024
	v_lshl_add_u64 v[6:7], v[6:7], 0, s[12:13]
	global_load_dwordx4 v[48:51], v[6:7], off offset:-2048
	global_load_dwordx4 v[52:55], v[6:7], off offset:-1024
	global_load_dwordx4 v[56:59], v[6:7], off
	global_load_dwordx4 v[60:63], v[6:7], off offset:1024
	v_lshl_add_u64 v[6:7], v[6:7], 0, s[12:13]
	global_load_dwordx4 v[64:67], v[6:7], off offset:-2048
	global_load_dwordx4 v[68:71], v[6:7], off offset:-1024
	global_load_dwordx4 v[72:75], v[6:7], off
	global_load_dwordx4 v[76:79], v[6:7], off offset:1024
	v_lshl_add_u64 v[6:7], v[6:7], 0, s[12:13]
	global_load_dwordx4 v[80:83], v[6:7], off offset:-2048
	global_load_dwordx4 v[84:87], v[6:7], off offset:-1024
	global_load_dwordx4 v[88:91], v[6:7], off
	global_load_dwordx4 v[92:95], v[6:7], off offset:1024
	v_lshl_add_u64 v[6:7], v[6:7], 0, s[12:13]
	global_load_dwordx4 v[96:99], v[6:7], off offset:-2048
	global_load_dwordx4 v[100:103], v[6:7], off offset:-1024
	global_load_dwordx4 v[104:107], v[6:7], off
	global_load_dwordx4 v[108:111], v[6:7], off offset:1024
	v_lshl_add_u64 v[6:7], v[6:7], 0, s[12:13]
	global_load_dwordx4 v[112:115], v[6:7], off offset:-2048
	global_load_dwordx4 v[116:119], v[6:7], off offset:-1024
	global_load_dwordx4 v[120:123], v[6:7], off
	global_load_dwordx4 v[124:127], v[6:7], off offset:1024
	v_lshl_add_u64 v[6:7], v[6:7], 0, s[12:13]
	global_load_dwordx4 v[128:131], v[6:7], off offset:-2048
	global_load_dwordx4 v[132:135], v[6:7], off offset:-1024
	global_load_dwordx4 v[136:139], v[6:7], off
	global_load_dwordx4 v[140:143], v[6:7], off offset:1024
	v_lshl_add_u64 v[6:7], v[6:7], 0, s[12:13]
	global_load_dwordx4 v[144:147], v[6:7], off offset:-2048
	global_load_dwordx4 v[148:151], v[6:7], off offset:-1024
	global_load_dwordx4 v[152:155], v[6:7], off
	global_load_dwordx4 v[156:159], v[6:7], off offset:1024
	v_lshl_add_u64 v[18:19], s[88:89], 0, v[4:5]
	v_add_co_u32_e32 v30, vcc, s3, v18
	s_nop 1
	v_addc_co_u32_e32 v31, vcc, 0, v19, vcc
	s_waitcnt vmcnt(31)
	v_cvt_pk_bf16_f32 v20, v32, v33
	v_cvt_pk_bf16_f32 v21, v34, v35
	global_store_dwordx2 v[30:31], v[20:21], off
	v_mul_f32_e32 v15, v33, v33
	v_fmac_f32_e32 v15, v32, v32
	v_fmac_f32_e32 v15, v34, v34
	v_fmac_f32_e32 v15, v35, v35
	s_waitcnt vmcnt(31)
	v_cvt_pk_bf16_f32 v22, v36, v37
	v_cvt_pk_bf16_f32 v23, v38, v39
	global_store_dwordx2 v[30:31], v[22:23], off offset:512
	v_mul_f32_e32 v14, v37, v37
	v_fmac_f32_e32 v14, v36, v36
	v_fmac_f32_e32 v14, v38, v38
	v_fmac_f32_e32 v14, v39, v39
	v_add_f32_e32 v14, v15, v14
	s_waitcnt vmcnt(31)
	v_cvt_pk_bf16_f32 v24, v40, v41
	v_cvt_pk_bf16_f32 v25, v42, v43
	global_store_dwordx2 v[30:31], v[24:25], off offset:1024
	v_mul_f32_e32 v15, v41, v41
	v_fmac_f32_e32 v15, v40, v40
	v_fmac_f32_e32 v15, v42, v42
	v_fmac_f32_e32 v15, v43, v43
	v_add_f32_e32 v14, v14, v15
	s_waitcnt vmcnt(31)
	v_cvt_pk_bf16_f32 v26, v44, v45
	v_cvt_pk_bf16_f32 v27, v46, v47
	global_store_dwordx2 v[30:31], v[26:27], off offset:1536
	v_mul_f32_e32 v15, v45, v45
	v_fmac_f32_e32 v15, v44, v44
	v_fmac_f32_e32 v15, v46, v46
	v_fmac_f32_e32 v15, v47, v47
	v_add_f32_e32 v14, v14, v15
	ds_bpermute_b32 v15, v8, v14
	s_waitcnt lgkmcnt(0)
	v_add_f32_e32 v14, v14, v15
	ds_bpermute_b32 v15, v9, v14
	s_waitcnt lgkmcnt(0)
	v_add_f32_e32 v14, v14, v15
	ds_bpermute_b32 v15, v10, v14
	s_waitcnt lgkmcnt(0)
	v_add_f32_e32 v14, v14, v15
	ds_bpermute_b32 v15, v11, v14
	s_waitcnt lgkmcnt(0)
	v_add_f32_e32 v14, v14, v15
	ds_bpermute_b32 v15, v12, v14
	s_waitcnt lgkmcnt(0)
	v_add_f32_e32 v14, v14, v15
	ds_bpermute_b32 v15, v13, v14
	s_waitcnt lgkmcnt(0)
	s_and_saveexec_b64 s[14:15], s[0:1]
	v_add_f32_e32 v14, v14, v15
	v_lshl_add_u64 v[16:17], s[88:89], 0, v[2:3]
	v_cndmask_b32_e64 v14, 0, v14, s[4:5]
	global_store_dword v[16:17], v14, off
	s_or_b64 exec, exec, s[14:15]
	v_lshl_add_u64 v[2:3], v[2:3], 0, s[6:7]
	v_lshl_add_u64 v[4:5], v[4:5], 0, s[10:11]
	v_lshl_add_u64 v[18:19], s[88:89], 0, v[4:5]
	v_add_co_u32_e32 v30, vcc, s3, v18
	s_nop 1
	v_addc_co_u32_e32 v31, vcc, 0, v19, vcc
	s_waitcnt vmcnt(32)
	v_cvt_pk_bf16_f32 v20, v48, v49
	v_cvt_pk_bf16_f32 v21, v50, v51
	global_store_dwordx2 v[30:31], v[20:21], off
	v_mul_f32_e32 v15, v49, v49
	v_fmac_f32_e32 v15, v48, v48
	v_fmac_f32_e32 v15, v50, v50
	v_fmac_f32_e32 v15, v51, v51
	s_waitcnt vmcnt(32)
	v_cvt_pk_bf16_f32 v22, v52, v53
	v_cvt_pk_bf16_f32 v23, v54, v55
	global_store_dwordx2 v[30:31], v[22:23], off offset:512
	v_mul_f32_e32 v14, v53, v53
	v_fmac_f32_e32 v14, v52, v52
	v_fmac_f32_e32 v14, v54, v54
	v_fmac_f32_e32 v14, v55, v55
	v_add_f32_e32 v14, v15, v14
	s_waitcnt vmcnt(32)
	v_cvt_pk_bf16_f32 v24, v56, v57
	v_cvt_pk_bf16_f32 v25, v58, v59
	global_store_dwordx2 v[30:31], v[24:25], off offset:1024
	v_mul_f32_e32 v15, v57, v57
	v_fmac_f32_e32 v15, v56, v56
	v_fmac_f32_e32 v15, v58, v58
	v_fmac_f32_e32 v15, v59, v59
	v_add_f32_e32 v14, v14, v15
	s_waitcnt vmcnt(32)
	v_cvt_pk_bf16_f32 v26, v60, v61
	v_cvt_pk_bf16_f32 v27, v62, v63
	global_store_dwordx2 v[30:31], v[26:27], off offset:1536
	v_mul_f32_e32 v15, v61, v61
	v_fmac_f32_e32 v15, v60, v60
	v_fmac_f32_e32 v15, v62, v62
	v_fmac_f32_e32 v15, v63, v63
	v_add_f32_e32 v14, v14, v15
	ds_bpermute_b32 v15, v8, v14
	s_waitcnt lgkmcnt(0)
	v_add_f32_e32 v14, v14, v15
	ds_bpermute_b32 v15, v9, v14
	s_waitcnt lgkmcnt(0)
	v_add_f32_e32 v14, v14, v15
	ds_bpermute_b32 v15, v10, v14
	s_waitcnt lgkmcnt(0)
	v_add_f32_e32 v14, v14, v15
	ds_bpermute_b32 v15, v11, v14
	s_waitcnt lgkmcnt(0)
	v_add_f32_e32 v14, v14, v15
	ds_bpermute_b32 v15, v12, v14
	s_waitcnt lgkmcnt(0)
	v_add_f32_e32 v14, v14, v15
	ds_bpermute_b32 v15, v13, v14
	s_waitcnt lgkmcnt(0)
	s_and_saveexec_b64 s[14:15], s[0:1]
	v_add_f32_e32 v14, v14, v15
	v_lshl_add_u64 v[16:17], s[88:89], 0, v[2:3]
	v_cndmask_b32_e64 v14, 0, v14, s[4:5]
	global_store_dword v[16:17], v14, off
	s_or_b64 exec, exec, s[14:15]
	v_lshl_add_u64 v[2:3], v[2:3], 0, s[6:7]
	v_lshl_add_u64 v[4:5], v[4:5], 0, s[10:11]
	v_lshl_add_u64 v[18:19], s[88:89], 0, v[4:5]
	v_add_co_u32_e32 v30, vcc, s3, v18
	s_nop 1
	v_addc_co_u32_e32 v31, vcc, 0, v19, vcc
	s_waitcnt vmcnt(33)
	v_cvt_pk_bf16_f32 v20, v64, v65
	v_cvt_pk_bf16_f32 v21, v66, v67
	global_store_dwordx2 v[30:31], v[20:21], off
	v_mul_f32_e32 v15, v65, v65
	v_fmac_f32_e32 v15, v64, v64
	v_fmac_f32_e32 v15, v66, v66
	v_fmac_f32_e32 v15, v67, v67
	s_waitcnt vmcnt(33)
	v_cvt_pk_bf16_f32 v22, v68, v69
	v_cvt_pk_bf16_f32 v23, v70, v71
	global_store_dwordx2 v[30:31], v[22:23], off offset:512
	v_mul_f32_e32 v14, v69, v69
	v_fmac_f32_e32 v14, v68, v68
	v_fmac_f32_e32 v14, v70, v70
	v_fmac_f32_e32 v14, v71, v71
	v_add_f32_e32 v14, v15, v14
	s_waitcnt vmcnt(33)
	v_cvt_pk_bf16_f32 v24, v72, v73
	v_cvt_pk_bf16_f32 v25, v74, v75
	global_store_dwordx2 v[30:31], v[24:25], off offset:1024
	v_mul_f32_e32 v15, v73, v73
	v_fmac_f32_e32 v15, v72, v72
	v_fmac_f32_e32 v15, v74, v74
	v_fmac_f32_e32 v15, v75, v75
	v_add_f32_e32 v14, v14, v15
	s_waitcnt vmcnt(33)
	v_cvt_pk_bf16_f32 v26, v76, v77
	v_cvt_pk_bf16_f32 v27, v78, v79
	global_store_dwordx2 v[30:31], v[26:27], off offset:1536
	v_mul_f32_e32 v15, v77, v77
	v_fmac_f32_e32 v15, v76, v76
	v_fmac_f32_e32 v15, v78, v78
	v_fmac_f32_e32 v15, v79, v79
	v_add_f32_e32 v14, v14, v15
	ds_bpermute_b32 v15, v8, v14
	s_waitcnt lgkmcnt(0)
	v_add_f32_e32 v14, v14, v15
	ds_bpermute_b32 v15, v9, v14
	s_waitcnt lgkmcnt(0)
	v_add_f32_e32 v14, v14, v15
	ds_bpermute_b32 v15, v10, v14
	s_waitcnt lgkmcnt(0)
	v_add_f32_e32 v14, v14, v15
	ds_bpermute_b32 v15, v11, v14
	s_waitcnt lgkmcnt(0)
	v_add_f32_e32 v14, v14, v15
	ds_bpermute_b32 v15, v12, v14
	s_waitcnt lgkmcnt(0)
	v_add_f32_e32 v14, v14, v15
	ds_bpermute_b32 v15, v13, v14
	s_waitcnt lgkmcnt(0)
	s_and_saveexec_b64 s[14:15], s[0:1]
	v_add_f32_e32 v14, v14, v15
	v_lshl_add_u64 v[16:17], s[88:89], 0, v[2:3]
	v_cndmask_b32_e64 v14, 0, v14, s[4:5]
	global_store_dword v[16:17], v14, off
	s_or_b64 exec, exec, s[14:15]
	v_lshl_add_u64 v[2:3], v[2:3], 0, s[6:7]
	v_lshl_add_u64 v[4:5], v[4:5], 0, s[10:11]
	v_lshl_add_u64 v[18:19], s[88:89], 0, v[4:5]
	v_add_co_u32_e32 v30, vcc, s3, v18
	s_nop 1
	v_addc_co_u32_e32 v31, vcc, 0, v19, vcc
	s_waitcnt vmcnt(34)
	v_cvt_pk_bf16_f32 v20, v80, v81
	v_cvt_pk_bf16_f32 v21, v82, v83
	global_store_dwordx2 v[30:31], v[20:21], off
	v_mul_f32_e32 v15, v81, v81
	v_fmac_f32_e32 v15, v80, v80
	v_fmac_f32_e32 v15, v82, v82
	v_fmac_f32_e32 v15, v83, v83
	s_waitcnt vmcnt(34)
	v_cvt_pk_bf16_f32 v22, v84, v85
	v_cvt_pk_bf16_f32 v23, v86, v87
	global_store_dwordx2 v[30:31], v[22:23], off offset:512
	v_mul_f32_e32 v14, v85, v85
	v_fmac_f32_e32 v14, v84, v84
	v_fmac_f32_e32 v14, v86, v86
	v_fmac_f32_e32 v14, v87, v87
	v_add_f32_e32 v14, v15, v14
	s_waitcnt vmcnt(34)
	v_cvt_pk_bf16_f32 v24, v88, v89
	v_cvt_pk_bf16_f32 v25, v90, v91
	global_store_dwordx2 v[30:31], v[24:25], off offset:1024
	v_mul_f32_e32 v15, v89, v89
	v_fmac_f32_e32 v15, v88, v88
	v_fmac_f32_e32 v15, v90, v90
	v_fmac_f32_e32 v15, v91, v91
	v_add_f32_e32 v14, v14, v15
	s_waitcnt vmcnt(34)
	v_cvt_pk_bf16_f32 v26, v92, v93
	v_cvt_pk_bf16_f32 v27, v94, v95
	global_store_dwordx2 v[30:31], v[26:27], off offset:1536
	v_mul_f32_e32 v15, v93, v93
	v_fmac_f32_e32 v15, v92, v92
	v_fmac_f32_e32 v15, v94, v94
	v_fmac_f32_e32 v15, v95, v95
	v_add_f32_e32 v14, v14, v15
	ds_bpermute_b32 v15, v8, v14
	s_waitcnt lgkmcnt(0)
	v_add_f32_e32 v14, v14, v15
	ds_bpermute_b32 v15, v9, v14
	s_waitcnt lgkmcnt(0)
	v_add_f32_e32 v14, v14, v15
	ds_bpermute_b32 v15, v10, v14
	s_waitcnt lgkmcnt(0)
	v_add_f32_e32 v14, v14, v15
	ds_bpermute_b32 v15, v11, v14
	s_waitcnt lgkmcnt(0)
	v_add_f32_e32 v14, v14, v15
	ds_bpermute_b32 v15, v12, v14
	s_waitcnt lgkmcnt(0)
	v_add_f32_e32 v14, v14, v15
	ds_bpermute_b32 v15, v13, v14
	s_waitcnt lgkmcnt(0)
	s_and_saveexec_b64 s[14:15], s[0:1]
	v_add_f32_e32 v14, v14, v15
	v_lshl_add_u64 v[16:17], s[88:89], 0, v[2:3]
	v_cndmask_b32_e64 v14, 0, v14, s[4:5]
	global_store_dword v[16:17], v14, off
	s_or_b64 exec, exec, s[14:15]
	v_lshl_add_u64 v[2:3], v[2:3], 0, s[6:7]
	v_lshl_add_u64 v[4:5], v[4:5], 0, s[10:11]
	v_lshl_add_u64 v[18:19], s[88:89], 0, v[4:5]
	v_add_co_u32_e32 v30, vcc, s3, v18
	s_nop 1
	v_addc_co_u32_e32 v31, vcc, 0, v19, vcc
	s_waitcnt vmcnt(35)
	v_cvt_pk_bf16_f32 v20, v96, v97
	v_cvt_pk_bf16_f32 v21, v98, v99
	global_store_dwordx2 v[30:31], v[20:21], off
	v_mul_f32_e32 v15, v97, v97
	v_fmac_f32_e32 v15, v96, v96
	v_fmac_f32_e32 v15, v98, v98
	v_fmac_f32_e32 v15, v99, v99
	s_waitcnt vmcnt(35)
	v_cvt_pk_bf16_f32 v22, v100, v101
	v_cvt_pk_bf16_f32 v23, v102, v103
	global_store_dwordx2 v[30:31], v[22:23], off offset:512
	v_mul_f32_e32 v14, v101, v101
	v_fmac_f32_e32 v14, v100, v100
	v_fmac_f32_e32 v14, v102, v102
	v_fmac_f32_e32 v14, v103, v103
	v_add_f32_e32 v14, v15, v14
	s_waitcnt vmcnt(35)
	v_cvt_pk_bf16_f32 v24, v104, v105
	v_cvt_pk_bf16_f32 v25, v106, v107
	global_store_dwordx2 v[30:31], v[24:25], off offset:1024
	v_mul_f32_e32 v15, v105, v105
	v_fmac_f32_e32 v15, v104, v104
	v_fmac_f32_e32 v15, v106, v106
	v_fmac_f32_e32 v15, v107, v107
	v_add_f32_e32 v14, v14, v15
	s_waitcnt vmcnt(35)
	v_cvt_pk_bf16_f32 v26, v108, v109
	v_cvt_pk_bf16_f32 v27, v110, v111
	global_store_dwordx2 v[30:31], v[26:27], off offset:1536
	v_mul_f32_e32 v15, v109, v109
	v_fmac_f32_e32 v15, v108, v108
	v_fmac_f32_e32 v15, v110, v110
	v_fmac_f32_e32 v15, v111, v111
	v_add_f32_e32 v14, v14, v15
	ds_bpermute_b32 v15, v8, v14
	s_waitcnt lgkmcnt(0)
	v_add_f32_e32 v14, v14, v15
	ds_bpermute_b32 v15, v9, v14
	s_waitcnt lgkmcnt(0)
	v_add_f32_e32 v14, v14, v15
	ds_bpermute_b32 v15, v10, v14
	s_waitcnt lgkmcnt(0)
	v_add_f32_e32 v14, v14, v15
	ds_bpermute_b32 v15, v11, v14
	s_waitcnt lgkmcnt(0)
	v_add_f32_e32 v14, v14, v15
	ds_bpermute_b32 v15, v12, v14
	s_waitcnt lgkmcnt(0)
	v_add_f32_e32 v14, v14, v15
	ds_bpermute_b32 v15, v13, v14
	s_waitcnt lgkmcnt(0)
	s_and_saveexec_b64 s[14:15], s[0:1]
	v_add_f32_e32 v14, v14, v15
	v_lshl_add_u64 v[16:17], s[88:89], 0, v[2:3]
	v_cndmask_b32_e64 v14, 0, v14, s[4:5]
	global_store_dword v[16:17], v14, off
	s_or_b64 exec, exec, s[14:15]
	v_lshl_add_u64 v[2:3], v[2:3], 0, s[6:7]
	v_lshl_add_u64 v[4:5], v[4:5], 0, s[10:11]
	v_lshl_add_u64 v[18:19], s[88:89], 0, v[4:5]
	v_add_co_u32_e32 v30, vcc, s3, v18
	s_nop 1
	v_addc_co_u32_e32 v31, vcc, 0, v19, vcc
	s_waitcnt vmcnt(36)
	v_cvt_pk_bf16_f32 v20, v112, v113
	v_cvt_pk_bf16_f32 v21, v114, v115
	global_store_dwordx2 v[30:31], v[20:21], off
	v_mul_f32_e32 v15, v113, v113
	v_fmac_f32_e32 v15, v112, v112
	v_fmac_f32_e32 v15, v114, v114
	v_fmac_f32_e32 v15, v115, v115
	s_waitcnt vmcnt(36)
	v_cvt_pk_bf16_f32 v22, v116, v117
	v_cvt_pk_bf16_f32 v23, v118, v119
	global_store_dwordx2 v[30:31], v[22:23], off offset:512
	v_mul_f32_e32 v14, v117, v117
	v_fmac_f32_e32 v14, v116, v116
	v_fmac_f32_e32 v14, v118, v118
	v_fmac_f32_e32 v14, v119, v119
	v_add_f32_e32 v14, v15, v14
	s_waitcnt vmcnt(36)
	v_cvt_pk_bf16_f32 v24, v120, v121
	v_cvt_pk_bf16_f32 v25, v122, v123
	global_store_dwordx2 v[30:31], v[24:25], off offset:1024
	v_mul_f32_e32 v15, v121, v121
	v_fmac_f32_e32 v15, v120, v120
	v_fmac_f32_e32 v15, v122, v122
	v_fmac_f32_e32 v15, v123, v123
	v_add_f32_e32 v14, v14, v15
	s_waitcnt vmcnt(36)
	v_cvt_pk_bf16_f32 v26, v124, v125
	v_cvt_pk_bf16_f32 v27, v126, v127
	global_store_dwordx2 v[30:31], v[26:27], off offset:1536
	v_mul_f32_e32 v15, v125, v125
	v_fmac_f32_e32 v15, v124, v124
	v_fmac_f32_e32 v15, v126, v126
	v_fmac_f32_e32 v15, v127, v127
	v_add_f32_e32 v14, v14, v15
	ds_bpermute_b32 v15, v8, v14
	s_waitcnt lgkmcnt(0)
	v_add_f32_e32 v14, v14, v15
	ds_bpermute_b32 v15, v9, v14
	s_waitcnt lgkmcnt(0)
	v_add_f32_e32 v14, v14, v15
	ds_bpermute_b32 v15, v10, v14
	s_waitcnt lgkmcnt(0)
	v_add_f32_e32 v14, v14, v15
	ds_bpermute_b32 v15, v11, v14
	s_waitcnt lgkmcnt(0)
	v_add_f32_e32 v14, v14, v15
	ds_bpermute_b32 v15, v12, v14
	s_waitcnt lgkmcnt(0)
	v_add_f32_e32 v14, v14, v15
	ds_bpermute_b32 v15, v13, v14
	s_waitcnt lgkmcnt(0)
	s_and_saveexec_b64 s[14:15], s[0:1]
	v_add_f32_e32 v14, v14, v15
	v_lshl_add_u64 v[16:17], s[88:89], 0, v[2:3]
	v_cndmask_b32_e64 v14, 0, v14, s[4:5]
	global_store_dword v[16:17], v14, off
	s_or_b64 exec, exec, s[14:15]
	v_lshl_add_u64 v[2:3], v[2:3], 0, s[6:7]
	v_lshl_add_u64 v[4:5], v[4:5], 0, s[10:11]
	v_lshl_add_u64 v[18:19], s[88:89], 0, v[4:5]
	v_add_co_u32_e32 v30, vcc, s3, v18
	s_nop 1
	v_addc_co_u32_e32 v31, vcc, 0, v19, vcc
	s_waitcnt vmcnt(37)
	v_cvt_pk_bf16_f32 v20, v128, v129
	v_cvt_pk_bf16_f32 v21, v130, v131
	global_store_dwordx2 v[30:31], v[20:21], off
	v_mul_f32_e32 v15, v129, v129
	v_fmac_f32_e32 v15, v128, v128
	v_fmac_f32_e32 v15, v130, v130
	v_fmac_f32_e32 v15, v131, v131
	s_waitcnt vmcnt(37)
	v_cvt_pk_bf16_f32 v22, v132, v133
	v_cvt_pk_bf16_f32 v23, v134, v135
	global_store_dwordx2 v[30:31], v[22:23], off offset:512
	v_mul_f32_e32 v14, v133, v133
	v_fmac_f32_e32 v14, v132, v132
	v_fmac_f32_e32 v14, v134, v134
	v_fmac_f32_e32 v14, v135, v135
	v_add_f32_e32 v14, v15, v14
	s_waitcnt vmcnt(37)
	v_cvt_pk_bf16_f32 v24, v136, v137
	v_cvt_pk_bf16_f32 v25, v138, v139
	global_store_dwordx2 v[30:31], v[24:25], off offset:1024
	v_mul_f32_e32 v15, v137, v137
	v_fmac_f32_e32 v15, v136, v136
	v_fmac_f32_e32 v15, v138, v138
	v_fmac_f32_e32 v15, v139, v139
	v_add_f32_e32 v14, v14, v15
	s_waitcnt vmcnt(37)
	v_cvt_pk_bf16_f32 v26, v140, v141
	v_cvt_pk_bf16_f32 v27, v142, v143
	global_store_dwordx2 v[30:31], v[26:27], off offset:1536
	v_mul_f32_e32 v15, v141, v141
	v_fmac_f32_e32 v15, v140, v140
	v_fmac_f32_e32 v15, v142, v142
	v_fmac_f32_e32 v15, v143, v143
	v_add_f32_e32 v14, v14, v15
	ds_bpermute_b32 v15, v8, v14
	s_waitcnt lgkmcnt(0)
	v_add_f32_e32 v14, v14, v15
	ds_bpermute_b32 v15, v9, v14
	s_waitcnt lgkmcnt(0)
	v_add_f32_e32 v14, v14, v15
	ds_bpermute_b32 v15, v10, v14
	s_waitcnt lgkmcnt(0)
	v_add_f32_e32 v14, v14, v15
	ds_bpermute_b32 v15, v11, v14
	s_waitcnt lgkmcnt(0)
	v_add_f32_e32 v14, v14, v15
	ds_bpermute_b32 v15, v12, v14
	s_waitcnt lgkmcnt(0)
	v_add_f32_e32 v14, v14, v15
	ds_bpermute_b32 v15, v13, v14
	s_waitcnt lgkmcnt(0)
	s_and_saveexec_b64 s[14:15], s[0:1]
	v_add_f32_e32 v14, v14, v15
	v_lshl_add_u64 v[16:17], s[88:89], 0, v[2:3]
	v_cndmask_b32_e64 v14, 0, v14, s[4:5]
	global_store_dword v[16:17], v14, off
	s_or_b64 exec, exec, s[14:15]
	v_lshl_add_u64 v[2:3], v[2:3], 0, s[6:7]
	v_lshl_add_u64 v[4:5], v[4:5], 0, s[10:11]
	v_lshl_add_u64 v[18:19], s[88:89], 0, v[4:5]
	v_add_co_u32_e32 v30, vcc, s3, v18
	s_nop 1
	v_addc_co_u32_e32 v31, vcc, 0, v19, vcc
	s_waitcnt vmcnt(38)
	v_cvt_pk_bf16_f32 v20, v144, v145
	v_cvt_pk_bf16_f32 v21, v146, v147
	global_store_dwordx2 v[30:31], v[20:21], off
	v_mul_f32_e32 v15, v145, v145
	v_fmac_f32_e32 v15, v144, v144
	v_fmac_f32_e32 v15, v146, v146
	v_fmac_f32_e32 v15, v147, v147
	s_waitcnt vmcnt(38)
	v_cvt_pk_bf16_f32 v22, v148, v149
	v_cvt_pk_bf16_f32 v23, v150, v151
	global_store_dwordx2 v[30:31], v[22:23], off offset:512
	v_mul_f32_e32 v14, v149, v149
	v_fmac_f32_e32 v14, v148, v148
	v_fmac_f32_e32 v14, v150, v150
	v_fmac_f32_e32 v14, v151, v151
	v_add_f32_e32 v14, v15, v14
	s_waitcnt vmcnt(38)
	v_cvt_pk_bf16_f32 v24, v152, v153
	v_cvt_pk_bf16_f32 v25, v154, v155
	global_store_dwordx2 v[30:31], v[24:25], off offset:1024
	v_mul_f32_e32 v15, v153, v153
	v_fmac_f32_e32 v15, v152, v152
	v_fmac_f32_e32 v15, v154, v154
	v_fmac_f32_e32 v15, v155, v155
	v_add_f32_e32 v14, v14, v15
	s_waitcnt vmcnt(38)
	v_cvt_pk_bf16_f32 v26, v156, v157
	v_cvt_pk_bf16_f32 v27, v158, v159
	global_store_dwordx2 v[30:31], v[26:27], off offset:1536
	v_mul_f32_e32 v15, v157, v157
	v_fmac_f32_e32 v15, v156, v156
	v_fmac_f32_e32 v15, v158, v158
	v_fmac_f32_e32 v15, v159, v159
	v_add_f32_e32 v14, v14, v15
	ds_bpermute_b32 v15, v8, v14
	s_waitcnt lgkmcnt(0)
	v_add_f32_e32 v14, v14, v15
	ds_bpermute_b32 v15, v9, v14
	s_waitcnt lgkmcnt(0)
	v_add_f32_e32 v14, v14, v15
	ds_bpermute_b32 v15, v10, v14
	s_waitcnt lgkmcnt(0)
	v_add_f32_e32 v14, v14, v15
	ds_bpermute_b32 v15, v11, v14
	s_waitcnt lgkmcnt(0)
	v_add_f32_e32 v14, v14, v15
	ds_bpermute_b32 v15, v12, v14
	s_waitcnt lgkmcnt(0)
	v_add_f32_e32 v14, v14, v15
	ds_bpermute_b32 v15, v13, v14
	s_waitcnt lgkmcnt(0)
	s_and_saveexec_b64 s[14:15], s[0:1]
	v_add_f32_e32 v14, v14, v15
	v_lshl_add_u64 v[16:17], s[88:89], 0, v[2:3]
	v_cndmask_b32_e64 v14, 0, v14, s[4:5]
	global_store_dword v[16:17], v14, off
	s_or_b64 exec, exec, s[14:15]
	.p2align 6
	s_nop 0
	s_nop 0
	s_nop 0
	s_nop 0
	s_nop 0
	s_nop 0
	s_nop 0
	s_nop 0
	s_nop 0
	s_nop 0
	s_nop 0
	s_nop 0
	s_nop 0
